# attention inner loop: V fragments prefetched into dead VGPRs v228-247, PV MFMAs issued back-to-back instead of read-wait-mfma ladder
# baseline (speedup 1.0000x reference)
.LBB0_597:
	v_cvt_pk_bf16_f32 v96, v112, v113
	v_cvt_pk_bf16_f32 v97, v116, v115
	v_cvt_pk_bf16_f32 v98, v118, v119
	v_cvt_pk_bf16_f32 v99, v120, v117
	v_cvt_pk_bf16_f32 v100, v114, v121
	v_cvt_pk_bf16_f32 v101, v122, v123
	v_cvt_pk_bf16_f32 v102, v124, v125
	v_cvt_pk_bf16_f32 v103, v126, v127
	ds_read_b64_tr_b16 v[104:105], v244 offset:61440
	ds_read_b64_tr_b16 v[106:107], v244 offset:63488
	ds_read_b64_tr_b16 v[108:109], v245 offset:61440
	ds_read_b64_tr_b16 v[110:111], v245 offset:63488
	ds_read_b64_tr_b16 v[112:113], v246 offset:61440
	ds_read_b64_tr_b16 v[114:115], v246 offset:63488
	ds_read_b64_tr_b16 v[116:117], v247 offset:61440
	ds_read_b64_tr_b16 v[118:119], v247 offset:63488
	v_mfma_f32_32x32x16_bf16 v[48:63], v[228:231], v[96:99], v[48:63]
	s_add_i32 s65, s65, 1
	s_add_u32 s36, s36, 0x10000
	s_addc_u32 s37, s37, 0
	s_addk_i32 s69, 0x4000
	s_add_i32 s70, s70, 64
	v_mfma_f32_32x32x16_bf16 v[32:47], v[232:235], v[96:99], v[32:47]
	s_add_u32 s38, s38, 0x10000
	s_addc_u32 s39, s39, 0
	s_add_i32 s71, s71, 1
	s_add_i32 s46, s46, 1
	v_add_f32_e32 v162, v163, v162
	s_cmp_eq_u32 s69, 0x100000
	v_mfma_f32_32x32x16_bf16 v[16:31], v[236:239], v[96:99], v[16:31]
	s_waitcnt vmcnt(0) lgkmcnt(0)
	s_barrier
	v_mfma_f32_32x32x16_bf16 v[0:15], v[240:243], v[96:99], v[0:15]
	v_mfma_f32_32x32x16_bf16 v[48:63], v[104:107], v[100:103], v[48:63]
	v_mfma_f32_32x32x16_bf16 v[32:47], v[108:111], v[100:103], v[32:47]
	v_mfma_f32_32x32x16_bf16 v[16:31], v[112:115], v[100:103], v[16:31]
	v_mfma_f32_32x32x16_bf16 v[0:15], v[116:119], v[100:103], v[0:15]
	s_cbranch_scc1 .LBB0_614

.LBB0_605:
	s_add_i32 s0, s69, 0xffffc000
	s_and_b32 s0, s0, 0x4000
	v_add_u32_e32 v244, s0, v176
	v_add_u32_e32 v245, s0, v177
	v_add_u32_e32 v246, s0, v178
	v_add_u32_e32 v247, s0, v179
	ds_read_b64_tr_b16 v[228:229], v244 offset:49152
	ds_read_b64_tr_b16 v[230:231], v244 offset:51200
	ds_read_b64_tr_b16 v[232:233], v245 offset:49152
	ds_read_b64_tr_b16 v[234:235], v245 offset:51200
	ds_read_b64_tr_b16 v[236:237], v246 offset:49152
	ds_read_b64_tr_b16 v[238:239], v246 offset:51200
	ds_read_b64_tr_b16 v[240:241], v247 offset:49152
	ds_read_b64_tr_b16 v[242:243], v247 offset:51200
	s_mul_hi_u32 s0, s46, 0xaaaaaaab
	s_lshr_b32 s0, s0, 1
	s_mul_i32 s0, s0, 0xffff4000
	v_add_u32_e32 v96, s0, v193
	v_add_u32_e32 v163, s69, v173
	v_add3_u32 v96, v96, v163, s57
	ds_read_b128 v[114:117], v96
	v_add_u32_e32 v122, s0, v191
	v_add3_u32 v122, v122, v163, s57
	ds_read_b128 v[122:125], v122
	v_add_u32_e32 v96, s0, v192
	v_add3_u32 v96, v96, v163, s57
	v_add_u32_e32 v126, s0, v190
	ds_read_b128 v[118:121], v96
	v_add3_u32 v126, v126, v163, s57
	ds_read_b128 v[206:209], v126
	s_waitcnt lgkmcnt(3)
	v_mfma_f32_32x32x16_bf16 v[96:111], v[114:117], v[140:143], v[64:79]
	v_exp_f32_e32 v112, v80
	v_exp_f32_e32 v113, v81
	v_exp_f32_e32 v114, v82
	v_exp_f32_e32 v115, v83
	v_exp_f32_e32 v116, v84
	v_exp_f32_e32 v117, v85
	s_waitcnt lgkmcnt(1)
	v_mfma_f32_32x32x16_bf16 v[96:111], v[118:121], v[136:139], v[96:111]
	v_exp_f32_e32 v118, v86
	v_exp_f32_e32 v119, v87
	v_exp_f32_e32 v120, v88
	v_exp_f32_e32 v121, v89
	v_mfma_f32_32x32x16_bf16 v[96:111], v[122:125], v[132:135], v[96:111]
	v_add_f32_e32 v123, 0, v112
	v_add_f32_e32 v123, v113, v123
	v_add_f32_e32 v123, v114, v123
	v_add_f32_e32 v123, v115, v123
	v_add_f32_e32 v123, v116, v123
	v_add_f32_e32 v123, v117, v123
	v_exp_f32_e32 v122, v90
	v_add_f32_e32 v123, v118, v123
	v_add_f32_e32 v123, v119, v123
	v_add_f32_e32 v123, v120, v123
	v_add_f32_e32 v123, v121, v123
	v_add_f32_e32 v124, v122, v123
	v_exp_f32_e32 v123, v91
	s_waitcnt lgkmcnt(0)
	v_mfma_f32_32x32x16_bf16 v[96:111], v[206:209], v[128:131], v[96:111]
	v_add_f32_e32 v125, v123, v124
	v_exp_f32_e32 v124, v92
	s_nop 0
	v_add_f32_e32 v126, v124, v125
	v_exp_f32_e32 v125, v93
	s_nop 0
	v_add_f32_e32 v127, v125, v126
	v_exp_f32_e32 v126, v94
	s_nop 0
	v_add_f32_e32 v164, v126, v127
	v_exp_f32_e32 v127, v95
	s_nop 0
	v_add_f32_e32 v209, v127, v164
	v_cmp_nge_f32_e32 vcc, s56, v209
	s_cbranch_vccz .LBB0_607
	v_max_f32_e32 v112, v81, v81
	v_max_f32_e32 v113, v80, v80
	v_max_f32_e32 v112, v113, v112
	v_max3_f32 v112, v112, v82, v83
	v_max3_f32 v112, v112, v84, v85
	v_max3_f32 v112, v112, v86, v87
	v_max3_f32 v112, v112, v88, v89
	v_max3_f32 v112, v112, v90, v91
	v_max3_f32 v112, v112, v92, v93
	v_max3_f32 v112, v112, v94, v95
	v_mov_b32_e32 v113, v112
	s_nop 1
	v_permlane32_swap_b32_e32 v112, v113
	v_max3_f32 v121, v112, v113, 0
	v_sub_f32_e32 v80, v80, v121
	v_exp_f32_e32 v112, v80
	v_sub_f32_e32 v81, v81, v121
	v_exp_f32_e32 v113, v81
	v_sub_f32_e32 v81, v82, v121
	v_exp_f32_e32 v114, v81
	v_sub_f32_e32 v81, v83, v121
	v_exp_f32_e32 v115, v81
	v_sub_f32_e32 v81, v84, v121
	v_add_f32_e32 v117, 0, v112
	v_exp_f32_e32 v116, v81
	v_sub_f32_e32 v82, v85, v121
	v_add_f32_e32 v81, v113, v117
	v_exp_f32_e32 v117, v82
	v_sub_f32_e32 v82, v86, v121
	v_add_f32_e32 v81, v114, v81
	v_exp_f32_e32 v118, v82
	v_sub_f32_e32 v82, v87, v121
	v_add_f32_e32 v81, v115, v81
	v_exp_f32_e32 v119, v82
	v_sub_f32_e32 v82, v88, v121
	v_add_f32_e32 v81, v116, v81
	v_sub_f32_e32 v83, v89, v121
	v_exp_f32_e32 v120, v82
	v_exp_f32_e64 v80, -v121
	v_sub_f32_e32 v84, v90, v121
	v_sub_f32_e32 v85, v91, v121
	v_sub_f32_e32 v86, v92, v121
	v_sub_f32_e32 v87, v93, v121
	v_sub_f32_e32 v88, v94, v121
	v_sub_f32_e32 v89, v95, v121
	v_add_f32_e32 v81, v117, v81
	v_sub_f32_e32 v111, v111, v121
	v_sub_f32_e32 v110, v110, v121
	v_sub_f32_e32 v109, v109, v121
	v_sub_f32_e32 v108, v108, v121
	v_sub_f32_e32 v107, v107, v121
	v_sub_f32_e32 v106, v106, v121
	v_sub_f32_e32 v105, v105, v121
	v_sub_f32_e32 v104, v104, v121
	v_sub_f32_e32 v103, v103, v121
	v_sub_f32_e32 v102, v102, v121
	v_sub_f32_e32 v101, v101, v121
	v_sub_f32_e32 v100, v100, v121
	v_sub_f32_e32 v99, v99, v121
	v_sub_f32_e32 v98, v98, v121
	v_sub_f32_e32 v97, v97, v121
	v_sub_f32_e32 v96, v96, v121
	v_sub_f32_e32 v79, v79, v121
	v_sub_f32_e32 v78, v78, v121
	v_sub_f32_e32 v77, v77, v121
	v_sub_f32_e32 v76, v76, v121
	v_sub_f32_e32 v75, v75, v121
	v_sub_f32_e32 v74, v74, v121
	v_sub_f32_e32 v73, v73, v121
	v_sub_f32_e32 v72, v72, v121
	v_sub_f32_e32 v71, v71, v121
	v_sub_f32_e32 v70, v70, v121
	v_sub_f32_e32 v69, v69, v121
	v_sub_f32_e32 v68, v68, v121
	v_sub_f32_e32 v67, v67, v121
	v_sub_f32_e32 v66, v66, v121
	v_sub_f32_e32 v65, v65, v121
	v_sub_f32_e32 v64, v64, v121
	v_exp_f32_e32 v121, v83
	v_add_f32_e32 v81, v118, v81
	v_exp_f32_e32 v122, v84
	v_add_f32_e32 v81, v119, v81
	v_exp_f32_e32 v123, v85
	v_add_f32_e32 v81, v120, v81
	v_exp_f32_e32 v124, v86
	v_pk_mul_f32 v[62:63], v[62:63], v[80:81] op_sel_hi:[1,0]
	v_pk_mul_f32 v[60:61], v[60:61], v[80:81] op_sel_hi:[1,0]
	v_pk_mul_f32 v[58:59], v[58:59], v[80:81] op_sel_hi:[1,0]
	v_pk_mul_f32 v[56:57], v[56:57], v[80:81] op_sel_hi:[1,0]
	v_pk_mul_f32 v[54:55], v[54:55], v[80:81] op_sel_hi:[1,0]
	v_pk_mul_f32 v[52:53], v[52:53], v[80:81] op_sel_hi:[1,0]
	v_pk_mul_f32 v[50:51], v[50:51], v[80:81] op_sel_hi:[1,0]
	v_pk_mul_f32 v[48:49], v[48:49], v[80:81] op_sel_hi:[1,0]
	v_pk_mul_f32 v[46:47], v[46:47], v[80:81] op_sel_hi:[1,0]
	v_pk_mul_f32 v[44:45], v[44:45], v[80:81] op_sel_hi:[1,0]
	v_pk_mul_f32 v[42:43], v[42:43], v[80:81] op_sel_hi:[1,0]
	v_pk_mul_f32 v[40:41], v[40:41], v[80:81] op_sel_hi:[1,0]
	v_pk_mul_f32 v[38:39], v[38:39], v[80:81] op_sel_hi:[1,0]
	v_pk_mul_f32 v[36:37], v[36:37], v[80:81] op_sel_hi:[1,0]
	v_pk_mul_f32 v[34:35], v[34:35], v[80:81] op_sel_hi:[1,0]
	v_pk_mul_f32 v[32:33], v[32:33], v[80:81] op_sel_hi:[1,0]
	v_pk_mul_f32 v[30:31], v[30:31], v[80:81] op_sel_hi:[1,0]
	v_pk_mul_f32 v[28:29], v[28:29], v[80:81] op_sel_hi:[1,0]
	v_pk_mul_f32 v[26:27], v[26:27], v[80:81] op_sel_hi:[1,0]
	v_pk_mul_f32 v[24:25], v[24:25], v[80:81] op_sel_hi:[1,0]
	v_pk_mul_f32 v[22:23], v[22:23], v[80:81] op_sel_hi:[1,0]
	v_pk_mul_f32 v[20:21], v[20:21], v[80:81] op_sel_hi:[1,0]
	v_pk_mul_f32 v[18:19], v[18:19], v[80:81] op_sel_hi:[1,0]
	v_pk_mul_f32 v[16:17], v[16:17], v[80:81] op_sel_hi:[1,0]
	v_pk_mul_f32 v[14:15], v[14:15], v[80:81] op_sel_hi:[1,0]
	v_pk_mul_f32 v[12:13], v[12:13], v[80:81] op_sel_hi:[1,0]
	v_pk_mul_f32 v[10:11], v[10:11], v[80:81] op_sel_hi:[1,0]
	v_pk_mul_f32 v[8:9], v[8:9], v[80:81] op_sel_hi:[1,0]
	v_pk_mul_f32 v[6:7], v[6:7], v[80:81] op_sel_hi:[1,0]
	v_pk_mul_f32 v[4:5], v[4:5], v[80:81] op_sel_hi:[1,0]
	v_pk_mul_f32 v[2:3], v[2:3], v[80:81] op_sel_hi:[1,0]
	v_pk_mul_f32 v[0:1], v[0:1], v[80:81] op_sel_hi:[1,0]
	v_mul_f32_e32 v162, v162, v80
	v_add_f32_e32 v80, v121, v81
	v_exp_f32_e32 v125, v87
	v_add_f32_e32 v80, v122, v80
	v_exp_f32_e32 v126, v88
	v_add_f32_e32 v80, v123, v80
	v_exp_f32_e32 v127, v89
	v_add_f32_e32 v80, v124, v80
	v_add_f32_e32 v80, v125, v80
	v_add_f32_e32 v80, v126, v80
	v_add_f32_e32 v209, v127, v80
.LBB0_607:
	v_cvt_pk_bf16_f32 v80, v112, v113
	v_cvt_pk_bf16_f32 v81, v114, v115
	v_cvt_pk_bf16_f32 v82, v116, v117
	v_cvt_pk_bf16_f32 v83, v118, v119
	ds_read_b64_tr_b16 v[88:89], v244 offset:53248
	ds_read_b64_tr_b16 v[90:91], v244 offset:55296
	ds_read_b64_tr_b16 v[92:93], v245 offset:53248
	ds_read_b64_tr_b16 v[94:95], v245 offset:55296
	v_cvt_pk_bf16_f32 v84, v120, v121
	v_cvt_pk_bf16_f32 v85, v122, v123
	v_cvt_pk_bf16_f32 v86, v124, v125
	v_cvt_pk_bf16_f32 v87, v126, v127
	ds_read_b64_tr_b16 v[112:113], v246 offset:53248
	ds_read_b64_tr_b16 v[114:115], v246 offset:55296
	ds_read_b64_tr_b16 v[116:117], v247 offset:53248
	ds_read_b64_tr_b16 v[118:119], v247 offset:55296
	v_mfma_f32_32x32x16_bf16 v[48:63], v[228:231], v[80:83], v[48:63]
	s_cmp_gt_u32 s70, s66
	s_cselect_b64 s[0:1], -1, 0
	s_and_b64 s[8:9], s[0:1], exec
	s_cselect_b32 s61, 2, 1
	v_mfma_f32_32x32x16_bf16 v[32:47], v[232:235], v[80:83], v[32:47]
	s_cmp_gt_i32 s70, s68
	s_cselect_b64 vcc, -1, 0
	s_and_b64 s[8:9], vcc, exec
	s_cselect_b32 s61, s61, 0
	v_mfma_f32_32x32x16_bf16 v[16:31], v[236:239], v[80:83], v[16:31]
	s_cmp_eq_u32 s61, s60
	v_mfma_f32_32x32x16_bf16 v[0:15], v[240:243], v[80:83], v[0:15]
	s_waitcnt lgkmcnt(6)
	v_mfma_f32_32x32x16_bf16 v[48:63], v[88:91], v[84:87], v[48:63]
	s_waitcnt lgkmcnt(4)
	v_mfma_f32_32x32x16_bf16 v[32:47], v[92:95], v[84:87], v[32:47]
	s_waitcnt lgkmcnt(2)
	v_mfma_f32_32x32x16_bf16 v[16:31], v[112:115], v[84:87], v[16:31]
	s_waitcnt lgkmcnt(0)
	v_mfma_f32_32x32x16_bf16 v[0:15], v[116:119], v[84:87], v[0:15]
	s_cbranch_scc1 .LBB0_609
	s_and_b64 s[8:9], vcc, s[0:1]
	v_cndmask_b32_e64 v80, 0, v161, s[8:9]
	s_cmp_eq_u32 s60, 0
	v_cndmask_b32_e32 v80, v160, v80, vcc
	s_cselect_b64 vcc, -1, 0
	s_cmp_eq_u32 s60, 2
	s_cselect_b64 s[8:9], -1, 0
	v_cndmask_b32_e64 v81, 0, v161, s[8:9]
	v_cndmask_b32_e32 v81, v81, v160, vcc
	v_sub_f32_e32 v80, v80, v81
	v_pk_add_f32 v[78:79], v[80:81], v[78:79] op_sel_hi:[0,1]
	v_pk_add_f32 v[76:77], v[80:81], v[76:77] op_sel_hi:[0,1]
	v_pk_add_f32 v[74:75], v[80:81], v[74:75] op_sel_hi:[0,1]
	v_pk_add_f32 v[72:73], v[80:81], v[72:73] op_sel_hi:[0,1]
	v_pk_add_f32 v[70:71], v[80:81], v[70:71] op_sel_hi:[0,1]
	v_pk_add_f32 v[68:69], v[80:81], v[68:69] op_sel_hi:[0,1]
	v_pk_add_f32 v[66:67], v[80:81], v[66:67] op_sel_hi:[0,1]
	v_pk_add_f32 v[64:65], v[80:81], v[64:65] op_sel_hi:[0,1]
	s_branch .LBB0_610

.LBB0_612:
	ds_read_b64_tr_b16 v[228:229], v244 offset:57344
	ds_read_b64_tr_b16 v[230:231], v244 offset:59392
	ds_read_b64_tr_b16 v[232:233], v245 offset:57344
	ds_read_b64_tr_b16 v[234:235], v245 offset:59392
	ds_read_b64_tr_b16 v[236:237], v246 offset:57344
	ds_read_b64_tr_b16 v[238:239], v246 offset:59392
	ds_read_b64_tr_b16 v[240:241], v247 offset:57344
	ds_read_b64_tr_b16 v[242:243], v247 offset:59392
	s_mul_hi_u32 s0, s71, 0xaaaaaaab
	s_lshr_b32 s0, s0, 1
	s_mul_i32 s0, s0, 0xffff4000
	v_add3_u32 v80, v193, s0, v163
	ds_read_b128 v[112:115], v80
	v_add3_u32 v80, v192, s0, v163
	ds_read_b128 v[120:123], v80
	v_exp_f32_e32 v116, v98
	v_exp_f32_e32 v118, v100
	v_exp_f32_e32 v119, v101
	v_exp_f32_e32 v117, v103
	v_add_f32_e32 v162, v209, v162
	s_waitcnt lgkmcnt(1)
	v_mfma_f32_32x32x16_bf16 v[80:95], v[112:115], v[140:143], v[64:79]
	v_exp_f32_e32 v112, v96
	v_exp_f32_e32 v113, v97
	v_exp_f32_e32 v115, v99
	v_add3_u32 v114, v191, s0, v163
	ds_read_b128 v[124:127], v114
	s_waitcnt lgkmcnt(1)
	v_mfma_f32_32x32x16_bf16 v[80:95], v[120:123], v[136:139], v[80:95]
	v_add_f32_e32 v123, 0, v112
	v_add_f32_e32 v123, v113, v123
	v_exp_f32_e32 v120, v102
	v_add_f32_e32 v123, v116, v123
	v_add3_u32 v122, v190, s0, v163
	v_add_f32_e32 v123, v115, v123
	ds_read_b128 v[210:213], v122
	v_exp_f32_e32 v114, v104
	v_add_f32_e32 v123, v118, v123
	v_exp_f32_e32 v121, v105
	v_add_f32_e32 v123, v119, v123
	v_exp_f32_e32 v122, v106
	v_add_f32_e32 v123, v120, v123
	v_add_f32_e32 v123, v117, v123
	v_add_f32_e32 v123, v114, v123
	v_add_f32_e32 v123, v121, v123
	s_waitcnt lgkmcnt(1)
	v_mfma_f32_32x32x16_bf16 v[80:95], v[124:127], v[132:135], v[80:95]
	v_add_f32_e32 v124, v122, v123
	v_exp_f32_e32 v123, v107
	s_nop 0
	v_add_f32_e32 v125, v123, v124
	v_exp_f32_e32 v124, v108
	s_waitcnt lgkmcnt(0)
	v_mfma_f32_32x32x16_bf16 v[80:95], v[210:213], v[128:131], v[80:95]
	v_add_f32_e32 v126, v124, v125
	v_exp_f32_e32 v125, v109
	s_nop 0
	v_add_f32_e32 v127, v125, v126
	v_exp_f32_e32 v126, v110
	s_nop 0
	v_add_f32_e32 v163, v126, v127
	v_exp_f32_e32 v127, v111
	s_nop 0
	v_add_f32_e32 v163, v127, v163
	v_cmp_nge_f32_e32 vcc, s56, v163
	s_cbranch_vccz .LBB0_597
	v_max_f32_e32 v112, v97, v97
	v_max_f32_e32 v113, v96, v96
	v_max_f32_e32 v112, v113, v112
	v_max3_f32 v112, v112, v98, v99
	v_max3_f32 v112, v112, v100, v101
	v_max3_f32 v112, v112, v102, v103
	v_max3_f32 v112, v112, v104, v105
	v_max3_f32 v112, v112, v106, v107
	v_max3_f32 v112, v112, v108, v109
	v_max3_f32 v112, v112, v110, v111
	v_mov_b32_e32 v113, v112
	s_nop 1
	v_permlane32_swap_b32_e32 v112, v113
	v_max3_f32 v121, v112, v113, 0
	v_sub_f32_e32 v96, v96, v121
	v_exp_f32_e32 v112, v96
	v_sub_f32_e32 v97, v97, v121
	v_exp_f32_e32 v113, v97
	v_sub_f32_e32 v97, v98, v121
	v_exp_f32_e32 v116, v97
	v_sub_f32_e32 v97, v99, v121
	v_exp_f32_e32 v115, v97
	v_sub_f32_e32 v97, v100, v121
	v_add_f32_e32 v114, 0, v112
	v_exp_f32_e32 v118, v97
	v_sub_f32_e32 v98, v101, v121
	v_add_f32_e32 v97, v113, v114
	v_exp_f32_e32 v119, v98
	v_sub_f32_e32 v98, v102, v121
	v_add_f32_e32 v97, v116, v97
	v_exp_f32_e32 v120, v98
	v_sub_f32_e32 v98, v103, v121
	v_add_f32_e32 v97, v115, v97
	v_exp_f32_e32 v117, v98
	v_sub_f32_e32 v98, v104, v121
	v_add_f32_e32 v97, v118, v97
	v_sub_f32_e32 v99, v105, v121
	v_exp_f32_e32 v114, v98
	v_exp_f32_e64 v96, -v121
	v_sub_f32_e32 v100, v106, v121
	v_sub_f32_e32 v101, v107, v121
	v_sub_f32_e32 v102, v108, v121
	v_sub_f32_e32 v103, v109, v121
	v_sub_f32_e32 v104, v110, v121
	v_sub_f32_e32 v105, v111, v121
	v_add_f32_e32 v97, v119, v97
	v_sub_f32_e32 v95, v95, v121
	v_sub_f32_e32 v94, v94, v121
	v_sub_f32_e32 v93, v93, v121
	v_sub_f32_e32 v92, v92, v121
	v_sub_f32_e32 v91, v91, v121
	v_sub_f32_e32 v90, v90, v121
	v_sub_f32_e32 v89, v89, v121
	v_sub_f32_e32 v88, v88, v121
	v_sub_f32_e32 v87, v87, v121
	v_sub_f32_e32 v86, v86, v121
	v_sub_f32_e32 v85, v85, v121
	v_sub_f32_e32 v84, v84, v121
	v_sub_f32_e32 v83, v83, v121
	v_sub_f32_e32 v82, v82, v121
	v_sub_f32_e32 v81, v81, v121
	v_sub_f32_e32 v80, v80, v121
	v_sub_f32_e32 v79, v79, v121
	v_sub_f32_e32 v78, v78, v121
	v_sub_f32_e32 v77, v77, v121
	v_sub_f32_e32 v76, v76, v121
	v_sub_f32_e32 v75, v75, v121
	v_sub_f32_e32 v74, v74, v121
	v_sub_f32_e32 v73, v73, v121
	v_sub_f32_e32 v72, v72, v121
	v_sub_f32_e32 v71, v71, v121
	v_sub_f32_e32 v70, v70, v121
	v_sub_f32_e32 v69, v69, v121
	v_sub_f32_e32 v68, v68, v121
	v_sub_f32_e32 v67, v67, v121
	v_sub_f32_e32 v66, v66, v121
	v_sub_f32_e32 v65, v65, v121
	v_sub_f32_e32 v64, v64, v121
	v_exp_f32_e32 v121, v99
	v_add_f32_e32 v97, v120, v97
	v_exp_f32_e32 v122, v100
	v_add_f32_e32 v97, v117, v97
	v_exp_f32_e32 v123, v101
	v_add_f32_e32 v97, v114, v97
	v_exp_f32_e32 v124, v102
	v_pk_mul_f32 v[62:63], v[62:63], v[96:97] op_sel_hi:[1,0]
	v_pk_mul_f32 v[60:61], v[60:61], v[96:97] op_sel_hi:[1,0]
	v_pk_mul_f32 v[58:59], v[58:59], v[96:97] op_sel_hi:[1,0]
	v_pk_mul_f32 v[56:57], v[56:57], v[96:97] op_sel_hi:[1,0]
	v_pk_mul_f32 v[54:55], v[54:55], v[96:97] op_sel_hi:[1,0]
	v_pk_mul_f32 v[52:53], v[52:53], v[96:97] op_sel_hi:[1,0]
	v_pk_mul_f32 v[50:51], v[50:51], v[96:97] op_sel_hi:[1,0]
	v_pk_mul_f32 v[48:49], v[48:49], v[96:97] op_sel_hi:[1,0]
	v_pk_mul_f32 v[46:47], v[46:47], v[96:97] op_sel_hi:[1,0]
	v_pk_mul_f32 v[44:45], v[44:45], v[96:97] op_sel_hi:[1,0]
	v_pk_mul_f32 v[42:43], v[42:43], v[96:97] op_sel_hi:[1,0]
	v_pk_mul_f32 v[40:41], v[40:41], v[96:97] op_sel_hi:[1,0]
	v_pk_mul_f32 v[38:39], v[38:39], v[96:97] op_sel_hi:[1,0]
	v_pk_mul_f32 v[36:37], v[36:37], v[96:97] op_sel_hi:[1,0]
	v_pk_mul_f32 v[34:35], v[34:35], v[96:97] op_sel_hi:[1,0]
	v_pk_mul_f32 v[32:33], v[32:33], v[96:97] op_sel_hi:[1,0]
	v_pk_mul_f32 v[30:31], v[30:31], v[96:97] op_sel_hi:[1,0]
	v_pk_mul_f32 v[28:29], v[28:29], v[96:97] op_sel_hi:[1,0]
	v_pk_mul_f32 v[26:27], v[26:27], v[96:97] op_sel_hi:[1,0]
	v_pk_mul_f32 v[24:25], v[24:25], v[96:97] op_sel_hi:[1,0]
	v_pk_mul_f32 v[22:23], v[22:23], v[96:97] op_sel_hi:[1,0]
	v_pk_mul_f32 v[20:21], v[20:21], v[96:97] op_sel_hi:[1,0]
	v_pk_mul_f32 v[18:19], v[18:19], v[96:97] op_sel_hi:[1,0]
	v_pk_mul_f32 v[16:17], v[16:17], v[96:97] op_sel_hi:[1,0]
	v_pk_mul_f32 v[14:15], v[14:15], v[96:97] op_sel_hi:[1,0]
	v_pk_mul_f32 v[12:13], v[12:13], v[96:97] op_sel_hi:[1,0]
	v_pk_mul_f32 v[10:11], v[10:11], v[96:97] op_sel_hi:[1,0]
	v_pk_mul_f32 v[8:9], v[8:9], v[96:97] op_sel_hi:[1,0]
	v_pk_mul_f32 v[6:7], v[6:7], v[96:97] op_sel_hi:[1,0]
	v_pk_mul_f32 v[4:5], v[4:5], v[96:97] op_sel_hi:[1,0]
	v_pk_mul_f32 v[2:3], v[2:3], v[96:97] op_sel_hi:[1,0]
	v_pk_mul_f32 v[0:1], v[0:1], v[96:97] op_sel_hi:[1,0]
	v_mul_f32_e32 v162, v162, v96
	v_add_f32_e32 v96, v121, v97
	v_exp_f32_e32 v125, v103
	v_add_f32_e32 v96, v122, v96
	v_exp_f32_e32 v126, v104
	v_add_f32_e32 v96, v123, v96
	v_exp_f32_e32 v127, v105
	v_add_f32_e32 v96, v124, v96
	v_add_f32_e32 v96, v125, v96
	v_add_f32_e32 v96, v126, v96
	v_add_f32_e32 v163, v127, v96
	s_branch .LBB0_597
